# second rmsnorm pass rewritten: software-pipelined row loads, DPP wave reduction
# speedup vs baseline: 1.0042x; 1.0042x over previous
.LBB0_527:
	s_or_b64 exec, exec, s[4:5]
	v_mov_b32_e32 v0, v154
	s_barrier
	s_mov_b32 s0, 0x600000
	v_add_u32_e32 v16, s76, v0
	v_cmp_gt_u32_e32 vcc, s0, v16
	s_and_saveexec_b64 s[6:7], vcc
	s_cbranch_execz .LBB0_540
	v_lshlrev_b32_e32 v0, 2, v0
	v_and_b32_e32 v20, 0xfc, v0
	v_lshlrev_b32_e32 v17, 2, v20
	global_load_dwordx4 v[0:3], v17, s[40:41] offset:3072
	global_load_dwordx4 v[4:7], v17, s[40:41] offset:2048
	global_load_dwordx4 v[8:11], v17, s[40:41] offset:1024
	global_load_dwordx4 v[12:15], v17, s[40:41]
	v_lshrrev_b32_e32 v18, 6, v16
	v_mbcnt_hi_u32_b32 v16, -1, v155
	v_and_b32_e32 v17, 64, v16
	v_add_u32_e32 v17, 64, v17
	v_xor_b32_e32 v19, 1, v16
	v_cmp_lt_i32_e32 vcc, v19, v17
	v_mov_b32_e32 v33, 0
	v_lshlrev_b32_e32 v32, 1, v20
	v_cndmask_b32_e32 v19, v16, v19, vcc
	v_lshlrev_b32_e32 v38, 2, v19
	v_xor_b32_e32 v19, 2, v16
	v_cmp_lt_i32_e32 vcc, v19, v17
	v_lshl_add_u64 v[34:35], s[42:43], 0, v[32:33]
	v_lshlrev_b32_e32 v36, 10, v18
	v_cndmask_b32_e32 v19, v16, v19, vcc
	v_lshlrev_b32_e32 v39, 2, v19
	v_xor_b32_e32 v19, 4, v16
	v_cmp_lt_i32_e32 vcc, v19, v17
	s_lshl_b32 s0, s3, 14
	s_lshl_b32 s1, s3, 13
	v_cndmask_b32_e32 v19, v16, v19, vcc
	v_lshlrev_b32_e32 v40, 2, v19
	v_xor_b32_e32 v19, 8, v16
	v_cmp_lt_i32_e32 vcc, v19, v17
	s_mov_b64 s[14:15], 0
	s_mov_b32 s20, 0xffff
	v_cndmask_b32_e32 v19, v16, v19, vcc
	v_lshlrev_b32_e32 v41, 2, v19
	v_xor_b32_e32 v19, 16, v16
	v_cmp_lt_i32_e32 vcc, v19, v17
	s_mov_b32 s21, 0x18000
	v_lshlrev_b32_e32 v32, 2, v20
	v_cndmask_b32_e32 v19, v16, v19, vcc
	v_lshlrev_b32_e32 v42, 2, v19
	v_xor_b32_e32 v19, 32, v16
	v_cmp_lt_i32_e32 vcc, v19, v17
	v_mov_b32_e32 v44, 0x358637bd
	s_mov_b32 s24, 0x800000
	v_cndmask_b32_e32 v16, v16, v19, vcc
	v_lshlrev_b32_e32 v43, 2, v16
	s_mov_b32 s25, 0x17fff
	s_cmp_lg_u32 s3, 0x100
	s_cbranch_scc1 .LBB0_530
	v_add_u32_e32 v80, 0x800000, v32
	v_lshrrev_b32_e32 v81, 1, v32
	v_add_u32_e32 v82, 0x400000, v81
	v_readfirstlane_b32 s24, v18
	s_sub_u32 s34, s24, 0x10000
	s_cmp_lt_u32 s24, 0x10000
	s_cselect_b32 s34, s24, s34
	s_cselect_b64 s[4:5], s[36:37], s[38:39]
	s_lshr_b32 s35, s34, 20
	s_lshl_b32 s34, s34, 12
	s_add_u32 s4, s4, s34
	s_addc_u32 s5, s5, s35
	global_load_dwordx4 v[16:19], v32, s[4:5]
	global_load_dwordx4 v[48:51], v80, s[4:5]
	global_load_dwordx4 v[20:23], v32, s[4:5] offset:1024
	global_load_dwordx4 v[52:55], v80, s[4:5] offset:1024
	global_load_dwordx4 v[24:27], v32, s[4:5] offset:2048
	global_load_dwordx4 v[56:59], v80, s[4:5] offset:2048
	global_load_dwordx4 v[28:31], v32, s[4:5] offset:3072
	global_load_dwordx4 v[60:63], v80, s[4:5] offset:3072
	s_add_u32 s25, s24, 0x1000
	s_sub_u32 s34, s25, 0x10000
	s_cmp_lt_u32 s25, 0x10000
	s_cselect_b32 s34, s25, s34
	s_cselect_b64 s[4:5], s[36:37], s[38:39]
	s_lshr_b32 s35, s34, 20
	s_lshl_b32 s34, s34, 12
	s_add_u32 s4, s4, s34
	s_addc_u32 s5, s5, s35
	global_load_dwordx4 v[84:87], v32, s[4:5]
	global_load_dwordx4 v[100:103], v80, s[4:5]
	global_load_dwordx4 v[88:91], v32, s[4:5] offset:1024
	global_load_dwordx4 v[104:107], v80, s[4:5] offset:1024
	global_load_dwordx4 v[92:95], v32, s[4:5] offset:2048
	global_load_dwordx4 v[108:111], v80, s[4:5] offset:2048
	global_load_dwordx4 v[96:99], v32, s[4:5] offset:3072
	global_load_dwordx4 v[112:115], v80, s[4:5] offset:3072
	s_waitcnt vmcnt(8)
	s_branch .Lrm2_pA
.Lrm2_topA:
	s_cmp_lt_u32 s25, 0x18000
	s_cbranch_scc0 .Lrm2_lastA
	s_sub_u32 s34, s25, 0x10000
	s_cmp_lt_u32 s25, 0x10000
	s_cselect_b32 s34, s25, s34
	s_cselect_b64 s[4:5], s[36:37], s[38:39]
	s_lshr_b32 s35, s34, 20
	s_lshl_b32 s34, s34, 12
	s_add_u32 s4, s4, s34
	s_addc_u32 s5, s5, s35
	global_load_dwordx4 v[84:87], v32, s[4:5]
	global_load_dwordx4 v[100:103], v80, s[4:5]
	global_load_dwordx4 v[88:91], v32, s[4:5] offset:1024
	global_load_dwordx4 v[104:107], v80, s[4:5] offset:1024
	global_load_dwordx4 v[92:95], v32, s[4:5] offset:2048
	global_load_dwordx4 v[108:111], v80, s[4:5] offset:2048
	global_load_dwordx4 v[96:99], v32, s[4:5] offset:3072
	global_load_dwordx4 v[112:115], v80, s[4:5] offset:3072
	s_waitcnt vmcnt(16)
	s_branch .Lrm2_pA

.Lrm2_pA:
	v_mul_f32_e32 v64, v16, v16
	v_mul_f32_e32 v66, v48, v48
	v_mul_f32_e32 v65, v17, v17
	v_mul_f32_e32 v67, v49, v49
	v_fmac_f32_e32 v64, v18, v18
	v_fmac_f32_e32 v66, v50, v50
	v_fmac_f32_e32 v65, v19, v19
	v_fmac_f32_e32 v67, v51, v51
	v_fmac_f32_e32 v64, v20, v20
	v_fmac_f32_e32 v66, v52, v52
	v_fmac_f32_e32 v65, v21, v21
	v_fmac_f32_e32 v67, v53, v53
	v_fmac_f32_e32 v64, v22, v22
	v_fmac_f32_e32 v66, v54, v54
	v_fmac_f32_e32 v65, v23, v23
	v_fmac_f32_e32 v67, v55, v55
	v_fmac_f32_e32 v64, v24, v24
	v_fmac_f32_e32 v66, v56, v56
	v_fmac_f32_e32 v65, v25, v25
	v_fmac_f32_e32 v67, v57, v57
	v_fmac_f32_e32 v64, v26, v26
	v_fmac_f32_e32 v66, v58, v58
	v_fmac_f32_e32 v65, v27, v27
	v_fmac_f32_e32 v67, v59, v59
	v_fmac_f32_e32 v64, v28, v28
	v_fmac_f32_e32 v66, v60, v60
	v_fmac_f32_e32 v65, v29, v29
	v_fmac_f32_e32 v67, v61, v61
	v_fmac_f32_e32 v64, v30, v30
	v_fmac_f32_e32 v66, v62, v62
	v_fmac_f32_e32 v65, v31, v31
	v_fmac_f32_e32 v67, v63, v63
	v_add_f32_e32 v64, v64, v65
	v_add_f32_e32 v66, v66, v67
	s_nop 1
	v_add_f32_dpp v64, v64, v64 quad_perm:[1,0,3,2] row_mask:0xf bank_mask:0xf bound_ctrl:1
	v_add_f32_dpp v66, v66, v66 quad_perm:[1,0,3,2] row_mask:0xf bank_mask:0xf bound_ctrl:1
	s_nop 1
	v_add_f32_dpp v64, v64, v64 quad_perm:[2,3,0,1] row_mask:0xf bank_mask:0xf bound_ctrl:1
	v_add_f32_dpp v66, v66, v66 quad_perm:[2,3,0,1] row_mask:0xf bank_mask:0xf bound_ctrl:1
	s_nop 1
	v_add_f32_dpp v64, v64, v64 row_half_mirror row_mask:0xf bank_mask:0xf bound_ctrl:1
	v_add_f32_dpp v66, v66, v66 row_half_mirror row_mask:0xf bank_mask:0xf bound_ctrl:1
	s_nop 1
	v_add_f32_dpp v64, v64, v64 row_mirror row_mask:0xf bank_mask:0xf bound_ctrl:1
	v_add_f32_dpp v66, v66, v66 row_mirror row_mask:0xf bank_mask:0xf bound_ctrl:1
	s_nop 1
	v_add_f32_dpp v64, v64, v64 row_bcast:15 row_mask:0xa bank_mask:0xf
	v_add_f32_dpp v66, v66, v66 row_bcast:15 row_mask:0xa bank_mask:0xf
	s_nop 1
	v_add_f32_dpp v64, v64, v64 row_bcast:31 row_mask:0xc bank_mask:0xf
	v_add_f32_dpp v66, v66, v66 row_bcast:31 row_mask:0xc bank_mask:0xf
	s_nop 1
	v_readlane_b32 s0, v64, 63
	v_readlane_b32 s1, v66, 63
	v_mov_b32_e32 v68, s0
	v_mov_b32_e32 v69, s1
	v_fmamk_f32 v68, v68, 0x3a800000, v44
	v_fmamk_f32 v69, v69, 0x3a800000, v44
	v_rsq_f32_e32 v68, v68
	v_rsq_f32_e32 v69, v69
	s_lshr_b32 s35, s24, 21
	s_lshl_b32 s34, s24, 11
	s_add_u32 s20, s42, s34
	s_addc_u32 s21, s43, s35
	v_mul_f32_e32 v16, v16, v68
	v_mul_f32_e32 v17, v17, v68
	v_mul_f32_e32 v18, v18, v68
	v_mul_f32_e32 v19, v19, v68
	v_mul_f32_e32 v20, v20, v68
	v_mul_f32_e32 v21, v21, v68
	v_mul_f32_e32 v22, v22, v68
	v_mul_f32_e32 v23, v23, v68
	v_mul_f32_e32 v24, v24, v68
	v_mul_f32_e32 v25, v25, v68
	v_mul_f32_e32 v26, v26, v68
	v_mul_f32_e32 v27, v27, v68
	v_mul_f32_e32 v28, v28, v68
	v_mul_f32_e32 v29, v29, v68
	v_mul_f32_e32 v30, v30, v68
	v_mul_f32_e32 v31, v31, v68
	v_mul_f32_e32 v48, v48, v69
	v_mul_f32_e32 v49, v49, v69
	v_mul_f32_e32 v50, v50, v69
	v_mul_f32_e32 v51, v51, v69
	v_mul_f32_e32 v52, v52, v69
	v_mul_f32_e32 v53, v53, v69
	v_mul_f32_e32 v54, v54, v69
	v_mul_f32_e32 v55, v55, v69
	v_mul_f32_e32 v56, v56, v69
	v_mul_f32_e32 v57, v57, v69
	v_mul_f32_e32 v58, v58, v69
	v_mul_f32_e32 v59, v59, v69
	v_mul_f32_e32 v60, v60, v69
	v_mul_f32_e32 v61, v61, v69
	v_mul_f32_e32 v62, v62, v69
	v_mul_f32_e32 v63, v63, v69
	v_mul_f32_e32 v16, v12, v16
	v_mul_f32_e32 v17, v13, v17
	v_mul_f32_e32 v18, v14, v18
	v_mul_f32_e32 v19, v15, v19
	v_mul_f32_e32 v20, v8, v20
	v_mul_f32_e32 v21, v9, v21
	v_mul_f32_e32 v22, v10, v22
	v_mul_f32_e32 v23, v11, v23
	v_mul_f32_e32 v24, v4, v24
	v_mul_f32_e32 v25, v5, v25
	v_mul_f32_e32 v26, v6, v26
	v_mul_f32_e32 v27, v7, v27
	v_mul_f32_e32 v28, v0, v28
	v_mul_f32_e32 v29, v1, v29
	v_mul_f32_e32 v30, v2, v30
	v_mul_f32_e32 v31, v3, v31
	v_mul_f32_e32 v48, v12, v48
	v_mul_f32_e32 v49, v13, v49
	v_mul_f32_e32 v50, v14, v50
	v_mul_f32_e32 v51, v15, v51
	v_mul_f32_e32 v52, v8, v52
	v_mul_f32_e32 v53, v9, v53
	v_mul_f32_e32 v54, v10, v54
	v_mul_f32_e32 v55, v11, v55
	v_mul_f32_e32 v56, v4, v56
	v_mul_f32_e32 v57, v5, v57
	v_mul_f32_e32 v58, v6, v58
	v_mul_f32_e32 v59, v7, v59
	v_mul_f32_e32 v60, v0, v60
	v_mul_f32_e32 v61, v1, v61
	v_mul_f32_e32 v62, v2, v62
	v_mul_f32_e32 v63, v3, v63
	v_cvt_pk_bf16_f32 v16, v16, v17
	v_cvt_pk_bf16_f32 v17, v18, v19
	v_cvt_pk_bf16_f32 v18, v20, v21
	v_cvt_pk_bf16_f32 v19, v22, v23
	v_cvt_pk_bf16_f32 v20, v24, v25
	v_cvt_pk_bf16_f32 v21, v26, v27
	v_cvt_pk_bf16_f32 v22, v28, v29
	v_cvt_pk_bf16_f32 v23, v30, v31
	v_cvt_pk_bf16_f32 v48, v48, v49
	v_cvt_pk_bf16_f32 v49, v50, v51
	v_cvt_pk_bf16_f32 v50, v52, v53
	v_cvt_pk_bf16_f32 v51, v54, v55
	v_cvt_pk_bf16_f32 v52, v56, v57
	v_cvt_pk_bf16_f32 v53, v58, v59
	v_cvt_pk_bf16_f32 v54, v60, v61
	v_cvt_pk_bf16_f32 v55, v62, v63
	global_store_dwordx2 v81, v[16:17], s[20:21]
	global_store_dwordx2 v82, v[48:49], s[20:21]
	global_store_dwordx2 v81, v[18:19], s[20:21] offset:512
	global_store_dwordx2 v82, v[50:51], s[20:21] offset:512
	global_store_dwordx2 v81, v[20:21], s[20:21] offset:1024
	global_store_dwordx2 v82, v[52:53], s[20:21] offset:1024
	global_store_dwordx2 v81, v[22:23], s[20:21] offset:1536
	global_store_dwordx2 v82, v[54:55], s[20:21] offset:1536
	s_mov_b32 s24, s25
	s_add_u32 s25, s25, 0x1000
	s_cmp_lt_u32 s24, 0x18000
	s_cbranch_scc0 .LBB0_540
.Lrm2_topB:
	s_cmp_lt_u32 s25, 0x18000
	s_cbranch_scc0 .Lrm2_lastB
	s_sub_u32 s34, s25, 0x10000
	s_cmp_lt_u32 s25, 0x10000
	s_cselect_b32 s34, s25, s34
	s_cselect_b64 s[4:5], s[36:37], s[38:39]
	s_lshr_b32 s35, s34, 20
	s_lshl_b32 s34, s34, 12
	s_add_u32 s4, s4, s34
	s_addc_u32 s5, s5, s35
	global_load_dwordx4 v[16:19], v32, s[4:5]
	global_load_dwordx4 v[48:51], v80, s[4:5]
	global_load_dwordx4 v[20:23], v32, s[4:5] offset:1024
	global_load_dwordx4 v[52:55], v80, s[4:5] offset:1024
	global_load_dwordx4 v[24:27], v32, s[4:5] offset:2048
	global_load_dwordx4 v[56:59], v80, s[4:5] offset:2048
	global_load_dwordx4 v[28:31], v32, s[4:5] offset:3072
	global_load_dwordx4 v[60:63], v80, s[4:5] offset:3072
	s_waitcnt vmcnt(16)
	s_branch .Lrm2_pB

.Lrm2_pB:
	v_mul_f32_e32 v64, v84, v84
	v_mul_f32_e32 v66, v100, v100
	v_mul_f32_e32 v65, v85, v85
	v_mul_f32_e32 v67, v101, v101
	v_fmac_f32_e32 v64, v86, v86
	v_fmac_f32_e32 v66, v102, v102
	v_fmac_f32_e32 v65, v87, v87
	v_fmac_f32_e32 v67, v103, v103
	v_fmac_f32_e32 v64, v88, v88
	v_fmac_f32_e32 v66, v104, v104
	v_fmac_f32_e32 v65, v89, v89
	v_fmac_f32_e32 v67, v105, v105
	v_fmac_f32_e32 v64, v90, v90
	v_fmac_f32_e32 v66, v106, v106
	v_fmac_f32_e32 v65, v91, v91
	v_fmac_f32_e32 v67, v107, v107
	v_fmac_f32_e32 v64, v92, v92
	v_fmac_f32_e32 v66, v108, v108
	v_fmac_f32_e32 v65, v93, v93
	v_fmac_f32_e32 v67, v109, v109
	v_fmac_f32_e32 v64, v94, v94
	v_fmac_f32_e32 v66, v110, v110
	v_fmac_f32_e32 v65, v95, v95
	v_fmac_f32_e32 v67, v111, v111
	v_fmac_f32_e32 v64, v96, v96
	v_fmac_f32_e32 v66, v112, v112
	v_fmac_f32_e32 v65, v97, v97
	v_fmac_f32_e32 v67, v113, v113
	v_fmac_f32_e32 v64, v98, v98
	v_fmac_f32_e32 v66, v114, v114
	v_fmac_f32_e32 v65, v99, v99
	v_fmac_f32_e32 v67, v115, v115
	v_add_f32_e32 v64, v64, v65
	v_add_f32_e32 v66, v66, v67
	s_nop 1
	v_add_f32_dpp v64, v64, v64 quad_perm:[1,0,3,2] row_mask:0xf bank_mask:0xf bound_ctrl:1
	v_add_f32_dpp v66, v66, v66 quad_perm:[1,0,3,2] row_mask:0xf bank_mask:0xf bound_ctrl:1
	s_nop 1
	v_add_f32_dpp v64, v64, v64 quad_perm:[2,3,0,1] row_mask:0xf bank_mask:0xf bound_ctrl:1
	v_add_f32_dpp v66, v66, v66 quad_perm:[2,3,0,1] row_mask:0xf bank_mask:0xf bound_ctrl:1
	s_nop 1
	v_add_f32_dpp v64, v64, v64 row_half_mirror row_mask:0xf bank_mask:0xf bound_ctrl:1
	v_add_f32_dpp v66, v66, v66 row_half_mirror row_mask:0xf bank_mask:0xf bound_ctrl:1
	s_nop 1
	v_add_f32_dpp v64, v64, v64 row_mirror row_mask:0xf bank_mask:0xf bound_ctrl:1
	v_add_f32_dpp v66, v66, v66 row_mirror row_mask:0xf bank_mask:0xf bound_ctrl:1
	s_nop 1
	v_add_f32_dpp v64, v64, v64 row_bcast:15 row_mask:0xa bank_mask:0xf
	v_add_f32_dpp v66, v66, v66 row_bcast:15 row_mask:0xa bank_mask:0xf
	s_nop 1
	v_add_f32_dpp v64, v64, v64 row_bcast:31 row_mask:0xc bank_mask:0xf
	v_add_f32_dpp v66, v66, v66 row_bcast:31 row_mask:0xc bank_mask:0xf
	s_nop 1
	v_readlane_b32 s0, v64, 63
	v_readlane_b32 s1, v66, 63
	v_mov_b32_e32 v68, s0
	v_mov_b32_e32 v69, s1
	v_fmamk_f32 v68, v68, 0x3a800000, v44
	v_fmamk_f32 v69, v69, 0x3a800000, v44
	v_rsq_f32_e32 v68, v68
	v_rsq_f32_e32 v69, v69
	s_lshr_b32 s35, s24, 21
	s_lshl_b32 s34, s24, 11
	s_add_u32 s20, s42, s34
	s_addc_u32 s21, s43, s35
	v_mul_f32_e32 v84, v84, v68
	v_mul_f32_e32 v85, v85, v68
	v_mul_f32_e32 v86, v86, v68
	v_mul_f32_e32 v87, v87, v68
	v_mul_f32_e32 v88, v88, v68
	v_mul_f32_e32 v89, v89, v68
	v_mul_f32_e32 v90, v90, v68
	v_mul_f32_e32 v91, v91, v68
	v_mul_f32_e32 v92, v92, v68
	v_mul_f32_e32 v93, v93, v68
	v_mul_f32_e32 v94, v94, v68
	v_mul_f32_e32 v95, v95, v68
	v_mul_f32_e32 v96, v96, v68
	v_mul_f32_e32 v97, v97, v68
	v_mul_f32_e32 v98, v98, v68
	v_mul_f32_e32 v99, v99, v68
	v_mul_f32_e32 v100, v100, v69
	v_mul_f32_e32 v101, v101, v69
	v_mul_f32_e32 v102, v102, v69
	v_mul_f32_e32 v103, v103, v69
	v_mul_f32_e32 v104, v104, v69
	v_mul_f32_e32 v105, v105, v69
	v_mul_f32_e32 v106, v106, v69
	v_mul_f32_e32 v107, v107, v69
	v_mul_f32_e32 v108, v108, v69
	v_mul_f32_e32 v109, v109, v69
	v_mul_f32_e32 v110, v110, v69
	v_mul_f32_e32 v111, v111, v69
	v_mul_f32_e32 v112, v112, v69
	v_mul_f32_e32 v113, v113, v69
	v_mul_f32_e32 v114, v114, v69
	v_mul_f32_e32 v115, v115, v69
	v_mul_f32_e32 v84, v12, v84
	v_mul_f32_e32 v85, v13, v85
	v_mul_f32_e32 v86, v14, v86
	v_mul_f32_e32 v87, v15, v87
	v_mul_f32_e32 v88, v8, v88
	v_mul_f32_e32 v89, v9, v89
	v_mul_f32_e32 v90, v10, v90
	v_mul_f32_e32 v91, v11, v91
	v_mul_f32_e32 v92, v4, v92
	v_mul_f32_e32 v93, v5, v93
	v_mul_f32_e32 v94, v6, v94
	v_mul_f32_e32 v95, v7, v95
	v_mul_f32_e32 v96, v0, v96
	v_mul_f32_e32 v97, v1, v97
	v_mul_f32_e32 v98, v2, v98
	v_mul_f32_e32 v99, v3, v99
	v_mul_f32_e32 v100, v12, v100
	v_mul_f32_e32 v101, v13, v101
	v_mul_f32_e32 v102, v14, v102
	v_mul_f32_e32 v103, v15, v103
	v_mul_f32_e32 v104, v8, v104
	v_mul_f32_e32 v105, v9, v105
	v_mul_f32_e32 v106, v10, v106
	v_mul_f32_e32 v107, v11, v107
	v_mul_f32_e32 v108, v4, v108
	v_mul_f32_e32 v109, v5, v109
	v_mul_f32_e32 v110, v6, v110
	v_mul_f32_e32 v111, v7, v111
	v_mul_f32_e32 v112, v0, v112
	v_mul_f32_e32 v113, v1, v113
	v_mul_f32_e32 v114, v2, v114
	v_mul_f32_e32 v115, v3, v115
	v_cvt_pk_bf16_f32 v84, v84, v85
	v_cvt_pk_bf16_f32 v85, v86, v87
	v_cvt_pk_bf16_f32 v86, v88, v89
	v_cvt_pk_bf16_f32 v87, v90, v91
	v_cvt_pk_bf16_f32 v88, v92, v93
	v_cvt_pk_bf16_f32 v89, v94, v95
	v_cvt_pk_bf16_f32 v90, v96, v97
	v_cvt_pk_bf16_f32 v91, v98, v99
	v_cvt_pk_bf16_f32 v100, v100, v101
	v_cvt_pk_bf16_f32 v101, v102, v103
	v_cvt_pk_bf16_f32 v102, v104, v105
	v_cvt_pk_bf16_f32 v103, v106, v107
	v_cvt_pk_bf16_f32 v104, v108, v109
	v_cvt_pk_bf16_f32 v105, v110, v111
	v_cvt_pk_bf16_f32 v106, v112, v113
	v_cvt_pk_bf16_f32 v107, v114, v115
	global_store_dwordx2 v81, v[84:85], s[20:21]
	global_store_dwordx2 v82, v[100:101], s[20:21]
	global_store_dwordx2 v81, v[86:87], s[20:21] offset:512
	global_store_dwordx2 v82, v[102:103], s[20:21] offset:512
	global_store_dwordx2 v81, v[88:89], s[20:21] offset:1024
	global_store_dwordx2 v82, v[104:105], s[20:21] offset:1024
	global_store_dwordx2 v81, v[90:91], s[20:21] offset:1536
	global_store_dwordx2 v82, v[106:107], s[20:21] offset:1536
	s_mov_b32 s24, s25
	s_add_u32 s25, s25, 0x1000
	s_cmp_lt_u32 s24, 0x18000
	s_cbranch_scc0 .LBB0_540
	s_branch .Lrm2_topA
